# grid barrier: non-leader workgroups poll the top-level generation word directly instead of the per-XCD generation (one hand-off hop less per barrier)
# speedup vs baseline: 1.0107x; 1.0042x over previous
; __device__ __forceinline__ unsigned xb_ld(unsigned* p)              { return __hip_atomic_load(p, __ATOMIC_RELAXED, __HIP_MEMORY_SCOPE_AGENT); }
; __device__ __forceinline__ unsigned xb_add(unsigned* p, unsigned v) { return __hip_atomic_fetch_add(p, v, __ATOMIC_RELAXED, __HIP_MEMORY_SCOPE_AGENT); }
; #define XB_SPIN(cond, bar) do { unsigned _sp = 0; while (cond) { __builtin_amdgcn_s_sleep(1); \
;     if ((++_sp & 255u) == 0u) { if (xb_ld(&(bar)[XB_TMO])) break; if (_sp > XB_SPIN_CAP) { atomicAdd(&(bar)[XB_TMO], 1u); break; } } } } while (0)
; __device__ __forceinline__ void xcd_barrier(const XcdBarrier& b) {
;     ...
;         const unsigned old = xb_add(&bar[XB_XSUB(b.x)], 1u);
;         const unsigned gen = old / nloc;
;         if (old + 1u == (gen + 1u) * nloc) {
;             __builtin_amdgcn_fence(__ATOMIC_RELEASE, "agent");
;             asm volatile("s_waitcnt vmcnt(0)" ::: "memory");
;             const unsigned og = xb_add(&bar[XB_TOP], 1u);
;             const unsigned tg = og / nx;
;             if (og + 1u == (tg + 1u) * nx) xb_add(&bar[XB_TOPGEN], 1u);
;             else XB_SPIN(xb_ld(&bar[XB_TOPGEN]) == tg, bar);
;             __builtin_amdgcn_fence(__ATOMIC_ACQUIRE, "agent");
;             xb_add(&bar[XB_XGEN(b.x)], 1u);
;             asm volatile("s_waitcnt vmcnt(0)" ::: "memory");
;         } else {
;             XB_SPIN(xb_ld(&bar[XB_XGEN(b.x)]) == gen, bar);
.LBB0_77:
	s_or_b64 exec, exec, s[8:9]
	v_cvt_f32_u32_e32 v4, v2
	s_waitcnt vmcnt(0)
	v_readfirstlane_b32 s6, v3
	v_sub_u32_e32 v3, 0, v2
	v_rcp_iflag_f32_e32 v4, v4
	v_add_u32_e32 v5, s6, v1
	v_mul_f32_e32 v4, 0x4f7ffffe, v4
	v_cvt_u32_f32_e32 v4, v4
	v_mul_lo_u32 v1, v3, v4
	v_mul_hi_u32 v1, v4, v1
	v_add_u32_e32 v1, v4, v1
	v_mul_hi_u32 v1, v5, v1
	v_mul_lo_u32 v3, v1, v2
	v_sub_u32_e32 v3, v5, v3
	v_add_u32_e32 v4, 1, v1
	v_cmp_ge_u32_e32 vcc, v3, v2
	s_nop 1
	v_cndmask_b32_e32 v1, v1, v4, vcc
	v_sub_u32_e32 v4, v3, v2
	v_cndmask_b32_e32 v3, v3, v4, vcc
	v_add_u32_e32 v4, 1, v1
	v_cmp_ge_u32_e32 vcc, v3, v2
	v_add_u32_e32 v3, 1, v5
	s_nop 0
	v_cndmask_b32_e32 v1, v1, v4, vcc
	v_mul_lo_u32 v4, v2, v1
	v_add_u32_e32 v2, v4, v2
	v_cmp_ne_u32_e32 vcc, v3, v2
	s_and_saveexec_b64 s[6:7], vcc
	s_xor_b64 s[6:7], exec, s[6:7]
	s_cbranch_execz .LBB0_91
	s_waitcnt lgkmcnt(0)
	s_add_u32 s34, s94, 0x43500
	s_addc_u32 s35, s95, 0
	v_mov_b32_e32 v0, 0
	global_load_dword v0, v0, s[34:35] sc1
	s_waitcnt vmcnt(0)
	v_cmp_eq_u32_e32 vcc, v0, v1
	s_and_saveexec_b64 s[8:9], vcc
	s_cbranch_execz .LBB0_90
	s_add_u32 s10, s94, 0x40200
	s_addc_u32 s11, s95, 0
	s_mov_b32 s18, 1
	s_mov_b64 s[36:37], 0
	v_mov_b32_e32 v0, 0
	s_branch .LBB0_81

; __device__ __forceinline__ unsigned xb_ld(unsigned* p)              { return __hip_atomic_load(p, __ATOMIC_RELAXED, __HIP_MEMORY_SCOPE_AGENT); }
; __device__ __forceinline__ unsigned xb_add(unsigned* p, unsigned v) { return __hip_atomic_fetch_add(p, v, __ATOMIC_RELAXED, __HIP_MEMORY_SCOPE_AGENT); }
; #define XB_SPIN(cond, bar) do { unsigned _sp = 0; while (cond) { __builtin_amdgcn_s_sleep(1); \
;     if ((++_sp & 255u) == 0u) { if (xb_ld(&(bar)[XB_TMO])) break; if (_sp > XB_SPIN_CAP) { atomicAdd(&(bar)[XB_TMO], 1u); break; } } } } while (0)
; __device__ __forceinline__ void xcd_barrier(const XcdBarrier& b) {
;     ...
;         const unsigned old = xb_add(&bar[XB_XSUB(b.x)], 1u);
;         const unsigned gen = old / nloc;
;         if (old + 1u == (gen + 1u) * nloc) {
;             __builtin_amdgcn_fence(__ATOMIC_RELEASE, "agent");
;             asm volatile("s_waitcnt vmcnt(0)" ::: "memory");
;             const unsigned og = xb_add(&bar[XB_TOP], 1u);
;             const unsigned tg = og / nx;
;             if (og + 1u == (tg + 1u) * nx) xb_add(&bar[XB_TOPGEN], 1u);
;             else XB_SPIN(xb_ld(&bar[XB_TOPGEN]) == tg, bar);
;             __builtin_amdgcn_fence(__ATOMIC_ACQUIRE, "agent");
;             xb_add(&bar[XB_XGEN(b.x)], 1u);
;             asm volatile("s_waitcnt vmcnt(0)" ::: "memory");
;         } else {
;             XB_SPIN(xb_ld(&bar[XB_XGEN(b.x)]) == gen, bar);
.LBB0_360:
	s_or_b64 exec, exec, s[8:9]
	v_cvt_f32_u32_e32 v4, v2
	s_waitcnt vmcnt(0)
	v_readfirstlane_b32 s6, v3
	v_sub_u32_e32 v3, 0, v2
	v_rcp_iflag_f32_e32 v4, v4
	v_add_u32_e32 v5, s6, v1
	v_mul_f32_e32 v4, 0x4f7ffffe, v4
	v_cvt_u32_f32_e32 v4, v4
	v_mul_lo_u32 v1, v3, v4
	v_mul_hi_u32 v1, v4, v1
	v_add_u32_e32 v1, v4, v1
	v_mul_hi_u32 v1, v5, v1
	v_mul_lo_u32 v3, v1, v2
	v_sub_u32_e32 v3, v5, v3
	v_add_u32_e32 v4, 1, v1
	v_cmp_ge_u32_e32 vcc, v3, v2
	s_nop 1
	v_cndmask_b32_e32 v1, v1, v4, vcc
	v_sub_u32_e32 v4, v3, v2
	v_cndmask_b32_e32 v3, v3, v4, vcc
	v_add_u32_e32 v4, 1, v1
	v_cmp_ge_u32_e32 vcc, v3, v2
	v_add_u32_e32 v3, 1, v5
	s_nop 0
	v_cndmask_b32_e32 v1, v1, v4, vcc
	v_mul_lo_u32 v4, v2, v1
	v_add_u32_e32 v2, v4, v2
	v_cmp_ne_u32_e32 vcc, v3, v2
	s_and_saveexec_b64 s[6:7], vcc
	s_xor_b64 s[6:7], exec, s[6:7]
	s_cbranch_execz .LBB0_374
	s_waitcnt lgkmcnt(0)
	s_add_u32 s34, s94, 0x43500
	s_addc_u32 s35, s95, 0
	v_mov_b32_e32 v0, 0
	global_load_dword v0, v0, s[34:35] sc1
	s_waitcnt vmcnt(0)
	v_cmp_eq_u32_e32 vcc, v0, v1
	s_and_saveexec_b64 s[8:9], vcc
	s_cbranch_execz .LBB0_373
	s_add_u32 s10, s94, 0x40200
	s_addc_u32 s11, s95, 0
	s_mov_b32 s18, 1
	s_mov_b64 s[48:49], 0
	v_mov_b32_e32 v0, 0
	s_branch .LBB0_364

; __device__ __forceinline__ unsigned xb_ld(unsigned* p)              { return __hip_atomic_load(p, __ATOMIC_RELAXED, __HIP_MEMORY_SCOPE_AGENT); }
; __device__ __forceinline__ unsigned xb_add(unsigned* p, unsigned v) { return __hip_atomic_fetch_add(p, v, __ATOMIC_RELAXED, __HIP_MEMORY_SCOPE_AGENT); }
; #define XB_SPIN(cond, bar) do { unsigned _sp = 0; while (cond) { __builtin_amdgcn_s_sleep(1); \
;     if ((++_sp & 255u) == 0u) { if (xb_ld(&(bar)[XB_TMO])) break; if (_sp > XB_SPIN_CAP) { atomicAdd(&(bar)[XB_TMO], 1u); break; } } } } while (0)
; __device__ __forceinline__ void xcd_barrier(const XcdBarrier& b) {
;     ...
;         const unsigned old = xb_add(&bar[XB_XSUB(b.x)], 1u);
;         const unsigned gen = old / nloc;
;         if (old + 1u == (gen + 1u) * nloc) {
;             __builtin_amdgcn_fence(__ATOMIC_RELEASE, "agent");
;             asm volatile("s_waitcnt vmcnt(0)" ::: "memory");
;             const unsigned og = xb_add(&bar[XB_TOP], 1u);
;             const unsigned tg = og / nx;
;             if (og + 1u == (tg + 1u) * nx) xb_add(&bar[XB_TOPGEN], 1u);
;             else XB_SPIN(xb_ld(&bar[XB_TOPGEN]) == tg, bar);
;             __builtin_amdgcn_fence(__ATOMIC_ACQUIRE, "agent");
;             xb_add(&bar[XB_XGEN(b.x)], 1u);
;             asm volatile("s_waitcnt vmcnt(0)" ::: "memory");
;         } else {
;             XB_SPIN(xb_ld(&bar[XB_XGEN(b.x)]) == gen, bar);
.LBB0_578:
	s_or_b64 exec, exec, s[10:11]
	v_cvt_f32_u32_e32 v4, v2
	s_waitcnt vmcnt(0)
	v_readfirstlane_b32 s8, v3
	v_sub_u32_e32 v3, 0, v2
	v_rcp_iflag_f32_e32 v4, v4
	v_add_u32_e32 v5, s8, v1
	v_mul_f32_e32 v4, 0x4f7ffffe, v4
	v_cvt_u32_f32_e32 v4, v4
	v_mul_lo_u32 v1, v3, v4
	v_mul_hi_u32 v1, v4, v1
	v_add_u32_e32 v1, v4, v1
	v_mul_hi_u32 v1, v5, v1
	v_mul_lo_u32 v3, v1, v2
	v_sub_u32_e32 v3, v5, v3
	v_add_u32_e32 v4, 1, v1
	v_cmp_ge_u32_e32 vcc, v3, v2
	s_nop 1
	v_cndmask_b32_e32 v1, v1, v4, vcc
	v_sub_u32_e32 v4, v3, v2
	v_cndmask_b32_e32 v3, v3, v4, vcc
	v_add_u32_e32 v4, 1, v1
	v_cmp_ge_u32_e32 vcc, v3, v2
	v_add_u32_e32 v3, 1, v5
	s_nop 0
	v_cndmask_b32_e32 v1, v1, v4, vcc
	v_mul_lo_u32 v4, v2, v1
	v_add_u32_e32 v2, v4, v2
	v_cmp_ne_u32_e32 vcc, v3, v2
	s_and_saveexec_b64 s[8:9], vcc
	s_xor_b64 s[8:9], exec, s[8:9]
	s_cbranch_execz .LBB0_592
	s_waitcnt lgkmcnt(0)
	s_add_u32 s38, s94, 0x43500
	s_addc_u32 s39, s95, 0
	v_mov_b32_e32 v0, 0
	global_load_dword v0, v0, s[38:39] sc1
	s_waitcnt vmcnt(0)
	v_cmp_eq_u32_e32 vcc, v0, v1
	s_and_saveexec_b64 s[10:11], vcc
	s_cbranch_execz .LBB0_591
	s_add_u32 s34, s94, 0x40200
	s_addc_u32 s35, s95, 0
	s_mov_b32 s18, 1
	s_mov_b64 s[42:43], 0
	v_mov_b32_e32 v0, 0
	s_branch .LBB0_582

; __device__ __forceinline__ unsigned xb_ld(unsigned* p)              { return __hip_atomic_load(p, __ATOMIC_RELAXED, __HIP_MEMORY_SCOPE_AGENT); }
; __device__ __forceinline__ unsigned xb_add(unsigned* p, unsigned v) { return __hip_atomic_fetch_add(p, v, __ATOMIC_RELAXED, __HIP_MEMORY_SCOPE_AGENT); }
; #define XB_SPIN(cond, bar) do { unsigned _sp = 0; while (cond) { __builtin_amdgcn_s_sleep(1); \
;     if ((++_sp & 255u) == 0u) { if (xb_ld(&(bar)[XB_TMO])) break; if (_sp > XB_SPIN_CAP) { atomicAdd(&(bar)[XB_TMO], 1u); break; } } } } while (0)
; __device__ __forceinline__ void xcd_barrier(const XcdBarrier& b) {
;     ...
;         const unsigned old = xb_add(&bar[XB_XSUB(b.x)], 1u);
;         const unsigned gen = old / nloc;
;         if (old + 1u == (gen + 1u) * nloc) {
;             __builtin_amdgcn_fence(__ATOMIC_RELEASE, "agent");
;             asm volatile("s_waitcnt vmcnt(0)" ::: "memory");
;             const unsigned og = xb_add(&bar[XB_TOP], 1u);
;             const unsigned tg = og / nx;
;             if (og + 1u == (tg + 1u) * nx) xb_add(&bar[XB_TOPGEN], 1u);
;             else XB_SPIN(xb_ld(&bar[XB_TOPGEN]) == tg, bar);
;             __builtin_amdgcn_fence(__ATOMIC_ACQUIRE, "agent");
;             xb_add(&bar[XB_XGEN(b.x)], 1u);
;             asm volatile("s_waitcnt vmcnt(0)" ::: "memory");
;         } else {
;             XB_SPIN(xb_ld(&bar[XB_XGEN(b.x)]) == gen, bar);
.LBB0_779:
	s_or_b64 exec, exec, s[12:13]
	v_cvt_f32_u32_e32 v4, v2
	s_waitcnt vmcnt(0)
	v_readfirstlane_b32 s10, v3
	v_sub_u32_e32 v3, 0, v2
	v_rcp_iflag_f32_e32 v4, v4
	v_add_u32_e32 v5, s10, v1
	v_mul_f32_e32 v4, 0x4f7ffffe, v4
	v_cvt_u32_f32_e32 v4, v4
	v_mul_lo_u32 v1, v3, v4
	v_mul_hi_u32 v1, v4, v1
	v_add_u32_e32 v1, v4, v1
	v_mul_hi_u32 v1, v5, v1
	v_mul_lo_u32 v3, v1, v2
	v_sub_u32_e32 v3, v5, v3
	v_add_u32_e32 v4, 1, v1
	v_cmp_ge_u32_e32 vcc, v3, v2
	s_nop 1
	v_cndmask_b32_e32 v1, v1, v4, vcc
	v_sub_u32_e32 v4, v3, v2
	v_cndmask_b32_e32 v3, v3, v4, vcc
	v_add_u32_e32 v4, 1, v1
	v_cmp_ge_u32_e32 vcc, v3, v2
	v_add_u32_e32 v3, 1, v5
	s_nop 0
	v_cndmask_b32_e32 v1, v1, v4, vcc
	v_mul_lo_u32 v4, v2, v1
	v_add_u32_e32 v2, v4, v2
	v_cmp_ne_u32_e32 vcc, v3, v2
	s_and_saveexec_b64 s[10:11], vcc
	s_xor_b64 s[10:11], exec, s[10:11]
	s_cbranch_execz .LBB0_793
	s_waitcnt lgkmcnt(0)
	s_add_u32 s42, s94, 0x43500
	s_addc_u32 s43, s95, 0
	v_mov_b32_e32 v0, 0
	global_load_dword v0, v0, s[42:43] sc1
	s_waitcnt vmcnt(0)
	v_cmp_eq_u32_e32 vcc, v0, v1
	s_and_saveexec_b64 s[34:35], vcc
	s_cbranch_execz .LBB0_792
	s_add_u32 s38, s94, 0x40200
	s_addc_u32 s39, s95, 0
	s_mov_b32 s19, 1
	s_mov_b64 s[48:49], 0
	v_mov_b32_e32 v0, 0
	s_branch .LBB0_783

; __device__ __forceinline__ unsigned xb_ld(unsigned* p)              { return __hip_atomic_load(p, __ATOMIC_RELAXED, __HIP_MEMORY_SCOPE_AGENT); }
; __device__ __forceinline__ unsigned xb_add(unsigned* p, unsigned v) { return __hip_atomic_fetch_add(p, v, __ATOMIC_RELAXED, __HIP_MEMORY_SCOPE_AGENT); }
; #define XB_SPIN(cond, bar) do { unsigned _sp = 0; while (cond) { __builtin_amdgcn_s_sleep(1); \
;     if ((++_sp & 255u) == 0u) { if (xb_ld(&(bar)[XB_TMO])) break; if (_sp > XB_SPIN_CAP) { atomicAdd(&(bar)[XB_TMO], 1u); break; } } } } while (0)
; __device__ __forceinline__ void xcd_barrier(const XcdBarrier& b) {
;     ...
;         const unsigned old = xb_add(&bar[XB_XSUB(b.x)], 1u);
;         const unsigned gen = old / nloc;
;         if (old + 1u == (gen + 1u) * nloc) {
;             __builtin_amdgcn_fence(__ATOMIC_RELEASE, "agent");
;             asm volatile("s_waitcnt vmcnt(0)" ::: "memory");
;             const unsigned og = xb_add(&bar[XB_TOP], 1u);
;             const unsigned tg = og / nx;
;             if (og + 1u == (tg + 1u) * nx) xb_add(&bar[XB_TOPGEN], 1u);
;             else XB_SPIN(xb_ld(&bar[XB_TOPGEN]) == tg, bar);
;             __builtin_amdgcn_fence(__ATOMIC_ACQUIRE, "agent");
;             xb_add(&bar[XB_XGEN(b.x)], 1u);
;             asm volatile("s_waitcnt vmcnt(0)" ::: "memory");
;         } else {
;             XB_SPIN(xb_ld(&bar[XB_XGEN(b.x)]) == gen, bar);
.LBB0_880:
	s_or_b64 exec, exec, s[8:9]
	v_cvt_f32_u32_e32 v4, v2
	s_waitcnt vmcnt(0)
	v_readfirstlane_b32 s6, v3
	v_sub_u32_e32 v3, 0, v2
	v_rcp_iflag_f32_e32 v4, v4
	v_add_u32_e32 v5, s6, v1
	v_mul_f32_e32 v4, 0x4f7ffffe, v4
	v_cvt_u32_f32_e32 v4, v4
	v_mul_lo_u32 v1, v3, v4
	v_mul_hi_u32 v1, v4, v1
	v_add_u32_e32 v1, v4, v1
	v_mul_hi_u32 v1, v5, v1
	v_mul_lo_u32 v3, v1, v2
	v_sub_u32_e32 v3, v5, v3
	v_add_u32_e32 v4, 1, v1
	v_cmp_ge_u32_e32 vcc, v3, v2
	s_nop 1
	v_cndmask_b32_e32 v1, v1, v4, vcc
	v_sub_u32_e32 v4, v3, v2
	v_cndmask_b32_e32 v3, v3, v4, vcc
	v_add_u32_e32 v4, 1, v1
	v_cmp_ge_u32_e32 vcc, v3, v2
	v_add_u32_e32 v3, 1, v5
	s_nop 0
	v_cndmask_b32_e32 v1, v1, v4, vcc
	v_mul_lo_u32 v4, v2, v1
	v_add_u32_e32 v2, v4, v2
	v_cmp_ne_u32_e32 vcc, v3, v2
	s_and_saveexec_b64 s[6:7], vcc
	s_xor_b64 s[6:7], exec, s[6:7]
	s_cbranch_execz .LBB0_894
	s_waitcnt lgkmcnt(0)
	s_add_u32 s16, s94, 0x43500
	s_addc_u32 s17, s95, 0
	v_mov_b32_e32 v0, 0
	global_load_dword v0, v0, s[16:17] sc1
	s_waitcnt vmcnt(0)
	v_cmp_eq_u32_e32 vcc, v0, v1
	s_and_saveexec_b64 s[8:9], vcc
	s_cbranch_execz .LBB0_893
	s_add_u32 s10, s94, 0x40200
	s_addc_u32 s11, s95, 0
	s_mov_b32 s21, 1
	s_mov_b64 s[18:19], 0
	v_mov_b32_e32 v0, 0
	s_branch .LBB0_884

; __device__ __forceinline__ unsigned xb_ld(unsigned* p)              { return __hip_atomic_load(p, __ATOMIC_RELAXED, __HIP_MEMORY_SCOPE_AGENT); }
; __device__ __forceinline__ unsigned xb_add(unsigned* p, unsigned v) { return __hip_atomic_fetch_add(p, v, __ATOMIC_RELAXED, __HIP_MEMORY_SCOPE_AGENT); }
; #define XB_SPIN(cond, bar) do { unsigned _sp = 0; while (cond) { __builtin_amdgcn_s_sleep(1); \
;     if ((++_sp & 255u) == 0u) { if (xb_ld(&(bar)[XB_TMO])) break; if (_sp > XB_SPIN_CAP) { atomicAdd(&(bar)[XB_TMO], 1u); break; } } } } while (0)
; __device__ __forceinline__ void xcd_barrier(const XcdBarrier& b) {
;     ...
;         const unsigned old = xb_add(&bar[XB_XSUB(b.x)], 1u);
;         const unsigned gen = old / nloc;
;         if (old + 1u == (gen + 1u) * nloc) {
;             __builtin_amdgcn_fence(__ATOMIC_RELEASE, "agent");
;             asm volatile("s_waitcnt vmcnt(0)" ::: "memory");
;             const unsigned og = xb_add(&bar[XB_TOP], 1u);
;             const unsigned tg = og / nx;
;             if (og + 1u == (tg + 1u) * nx) xb_add(&bar[XB_TOPGEN], 1u);
;             else XB_SPIN(xb_ld(&bar[XB_TOPGEN]) == tg, bar);
;             __builtin_amdgcn_fence(__ATOMIC_ACQUIRE, "agent");
;             xb_add(&bar[XB_XGEN(b.x)], 1u);
;             asm volatile("s_waitcnt vmcnt(0)" ::: "memory");
;         } else {
;             XB_SPIN(xb_ld(&bar[XB_XGEN(b.x)]) == gen, bar);
.LBB0_967:
	s_or_b64 exec, exec, s[8:9]
	v_cvt_f32_u32_e32 v4, v2
	s_waitcnt vmcnt(0)
	v_readfirstlane_b32 s6, v3
	v_sub_u32_e32 v3, 0, v2
	v_rcp_iflag_f32_e32 v4, v4
	v_add_u32_e32 v5, s6, v1
	v_mul_f32_e32 v4, 0x4f7ffffe, v4
	v_cvt_u32_f32_e32 v4, v4
	v_mul_lo_u32 v1, v3, v4
	v_mul_hi_u32 v1, v4, v1
	v_add_u32_e32 v1, v4, v1
	v_mul_hi_u32 v1, v5, v1
	v_mul_lo_u32 v3, v1, v2
	v_sub_u32_e32 v3, v5, v3
	v_add_u32_e32 v4, 1, v1
	v_cmp_ge_u32_e32 vcc, v3, v2
	s_nop 1
	v_cndmask_b32_e32 v1, v1, v4, vcc
	v_sub_u32_e32 v4, v3, v2
	v_cndmask_b32_e32 v3, v3, v4, vcc
	v_add_u32_e32 v4, 1, v1
	v_cmp_ge_u32_e32 vcc, v3, v2
	v_add_u32_e32 v3, 1, v5
	s_nop 0
	v_cndmask_b32_e32 v1, v1, v4, vcc
	v_mul_lo_u32 v4, v2, v1
	v_add_u32_e32 v2, v4, v2
	v_cmp_ne_u32_e32 vcc, v3, v2
	s_and_saveexec_b64 s[6:7], vcc
	s_xor_b64 s[6:7], exec, s[6:7]
	s_cbranch_execz .LBB0_981
	s_waitcnt lgkmcnt(0)
	s_add_u32 s42, s94, 0x43500
	s_addc_u32 s43, s95, 0
	v_mov_b32_e32 v0, 0
	global_load_dword v0, v0, s[42:43] sc1
	s_waitcnt vmcnt(0)
	v_cmp_eq_u32_e32 vcc, v0, v1
	s_and_saveexec_b64 s[8:9], vcc
	s_cbranch_execz .LBB0_980
	s_add_u32 s34, s94, 0x40200
	s_addc_u32 s35, s95, 0
	s_mov_b32 s20, 1
	s_mov_b64 s[44:45], 0
	v_mov_b32_e32 v0, 0
	s_branch .LBB0_971

; __device__ __forceinline__ unsigned xb_ld(unsigned* p)              { return __hip_atomic_load(p, __ATOMIC_RELAXED, __HIP_MEMORY_SCOPE_AGENT); }
; __device__ __forceinline__ unsigned xb_add(unsigned* p, unsigned v) { return __hip_atomic_fetch_add(p, v, __ATOMIC_RELAXED, __HIP_MEMORY_SCOPE_AGENT); }
; #define XB_SPIN(cond, bar) do { unsigned _sp = 0; while (cond) { __builtin_amdgcn_s_sleep(1); \
;     if ((++_sp & 255u) == 0u) { if (xb_ld(&(bar)[XB_TMO])) break; if (_sp > XB_SPIN_CAP) { atomicAdd(&(bar)[XB_TMO], 1u); break; } } } } while (0)
; __device__ __forceinline__ void xcd_barrier(const XcdBarrier& b) {
;     ...
;         const unsigned old = xb_add(&bar[XB_XSUB(b.x)], 1u);
;         const unsigned gen = old / nloc;
;         if (old + 1u == (gen + 1u) * nloc) {
;             __builtin_amdgcn_fence(__ATOMIC_RELEASE, "agent");
;             asm volatile("s_waitcnt vmcnt(0)" ::: "memory");
;             const unsigned og = xb_add(&bar[XB_TOP], 1u);
;             const unsigned tg = og / nx;
;             if (og + 1u == (tg + 1u) * nx) xb_add(&bar[XB_TOPGEN], 1u);
;             else XB_SPIN(xb_ld(&bar[XB_TOPGEN]) == tg, bar);
;             __builtin_amdgcn_fence(__ATOMIC_ACQUIRE, "agent");
;             xb_add(&bar[XB_XGEN(b.x)], 1u);
;             asm volatile("s_waitcnt vmcnt(0)" ::: "memory");
;         } else {
;             XB_SPIN(xb_ld(&bar[XB_XGEN(b.x)]) == gen, bar);
.LBB0_1035:
	s_or_b64 exec, exec, s[8:9]
	v_cvt_f32_u32_e32 v4, v2
	s_waitcnt vmcnt(0)
	v_readfirstlane_b32 s3, v3
	v_sub_u32_e32 v3, 0, v2
	v_rcp_iflag_f32_e32 v4, v4
	v_add_u32_e32 v5, s3, v1
	v_mul_f32_e32 v4, 0x4f7ffffe, v4
	v_cvt_u32_f32_e32 v4, v4
	v_mul_lo_u32 v1, v3, v4
	v_mul_hi_u32 v1, v4, v1
	v_add_u32_e32 v1, v4, v1
	v_mul_hi_u32 v1, v5, v1
	v_mul_lo_u32 v3, v1, v2
	v_sub_u32_e32 v3, v5, v3
	v_add_u32_e32 v4, 1, v1
	v_cmp_ge_u32_e32 vcc, v3, v2
	s_nop 1
	v_cndmask_b32_e32 v1, v1, v4, vcc
	v_sub_u32_e32 v4, v3, v2
	v_cndmask_b32_e32 v3, v3, v4, vcc
	v_add_u32_e32 v4, 1, v1
	v_cmp_ge_u32_e32 vcc, v3, v2
	v_add_u32_e32 v3, 1, v5
	s_nop 0
	v_cndmask_b32_e32 v1, v1, v4, vcc
	v_mul_lo_u32 v4, v2, v1
	v_add_u32_e32 v2, v4, v2
	v_cmp_ne_u32_e32 vcc, v3, v2
	s_and_saveexec_b64 s[6:7], vcc
	s_xor_b64 s[6:7], exec, s[6:7]
	s_cbranch_execz .LBB0_1049
	s_waitcnt lgkmcnt(0)
	s_add_u32 s16, s94, 0x43500
	s_addc_u32 s17, s95, 0
	v_mov_b32_e32 v0, 0
	global_load_dword v0, v0, s[16:17] sc1
	s_waitcnt vmcnt(0)
	v_cmp_eq_u32_e32 vcc, v0, v1
	s_and_saveexec_b64 s[8:9], vcc
	s_cbranch_execz .LBB0_1048
	s_add_u32 s14, s94, 0x40200
	s_addc_u32 s15, s95, 0
	s_mov_b32 s3, 1
	s_mov_b64 s[18:19], 0
	v_mov_b32_e32 v0, 0
	s_branch .LBB0_1039
